# grid barrier: released workgroups poll the cross-XCC generation word directly (skips the XCC leader poll + per-XCC release hop); arrival/write-back/acquire unchanged
# baseline (speedup 1.0000x reference)
.LBB0_132:
	s_or_b64 exec, exec, s[12:13]
	v_cvt_f32_u32_e32 v4, v2
	s_waitcnt vmcnt(0)
	v_readfirstlane_b32 s2, v3
	v_sub_u32_e32 v3, 0, v2
	v_rcp_iflag_f32_e32 v4, v4
	v_add_u32_e32 v5, s2, v1
	v_mul_f32_e32 v4, 0x4f7ffffe, v4
	v_cvt_u32_f32_e32 v4, v4
	v_mul_lo_u32 v1, v3, v4
	v_mul_hi_u32 v1, v4, v1
	v_add_u32_e32 v1, v4, v1
	v_mul_hi_u32 v1, v5, v1
	v_mul_lo_u32 v3, v1, v2
	v_sub_u32_e32 v3, v5, v3
	v_add_u32_e32 v4, 1, v1
	v_cmp_ge_u32_e32 vcc, v3, v2
	s_nop 1
	v_cndmask_b32_e32 v1, v1, v4, vcc
	v_sub_u32_e32 v4, v3, v2
	v_cndmask_b32_e32 v3, v3, v4, vcc
	v_add_u32_e32 v4, 1, v1
	v_cmp_ge_u32_e32 vcc, v3, v2
	v_add_u32_e32 v3, 1, v5
	s_nop 0
	v_cndmask_b32_e32 v1, v1, v4, vcc
	v_mul_lo_u32 v4, v2, v1
	v_add_u32_e32 v2, v4, v2
	v_cmp_ne_u32_e32 vcc, v3, v2
	s_and_saveexec_b64 s[2:3], vcc
	s_xor_b64 s[10:11], exec, s[2:3]
	s_cbranch_execz .LBB0_146
	s_waitcnt lgkmcnt(0)
	v_mov_b32_e32 v0, 0
	buffer_inv sc1
	s_add_u32 s16, s6, 0x13500
	s_addc_u32 s17, s7, 0
	global_load_dword v0, v0, s[16:17] sc1
	s_waitcnt vmcnt(0)
	v_cmp_eq_u32_e32 vcc, v0, v1
	s_and_saveexec_b64 s[12:13], vcc
	s_cbranch_execz .LBB0_145
	s_add_u32 s14, s6, 0x10200
	s_addc_u32 s15, s7, 0
	s_mov_b32 s2, 1
	s_mov_b64 s[18:19], 0
	v_mov_b32_e32 v0, 0
	s_branch .LBB0_136

.LBB0_209:
	s_or_b64 exec, exec, s[12:13]
	v_cvt_f32_u32_e32 v5, v3
	s_waitcnt vmcnt(0)
	v_readfirstlane_b32 s10, v4
	v_sub_u32_e32 v4, 0, v3
	v_rcp_iflag_f32_e32 v5, v5
	v_add_u32_e32 v6, s10, v1
	v_mul_f32_e32 v5, 0x4f7ffffe, v5
	v_cvt_u32_f32_e32 v5, v5
	v_mul_lo_u32 v1, v4, v5
	v_mul_hi_u32 v1, v5, v1
	v_add_u32_e32 v1, v5, v1
	v_mul_hi_u32 v1, v6, v1
	v_mul_lo_u32 v4, v1, v3
	v_sub_u32_e32 v4, v6, v4
	v_add_u32_e32 v5, 1, v1
	v_cmp_ge_u32_e32 vcc, v4, v3
	s_nop 1
	v_cndmask_b32_e32 v1, v1, v5, vcc
	v_sub_u32_e32 v5, v4, v3
	v_cndmask_b32_e32 v4, v4, v5, vcc
	v_add_u32_e32 v5, 1, v1
	v_cmp_ge_u32_e32 vcc, v4, v3
	v_add_u32_e32 v4, 1, v6
	s_nop 0
	v_cndmask_b32_e32 v1, v1, v5, vcc
	v_mul_lo_u32 v5, v3, v1
	v_add_u32_e32 v3, v5, v3
	v_cmp_ne_u32_e32 vcc, v4, v3
	s_and_saveexec_b64 s[10:11], vcc
	s_xor_b64 s[10:11], exec, s[10:11]
	s_cbranch_execz .LBB0_223
	s_waitcnt lgkmcnt(0)
	v_mov_b32_e32 v2, 0
	buffer_inv sc1
	s_add_u32 s16, s6, 0x13500
	s_addc_u32 s17, s7, 0
	global_load_dword v2, v2, s[16:17] sc1
	s_waitcnt vmcnt(0)
	v_cmp_eq_u32_e32 vcc, v2, v1
	s_and_saveexec_b64 s[12:13], vcc
	s_cbranch_execz .LBB0_222
	s_add_u32 s14, s6, 0x10200
	s_addc_u32 s15, s7, 0
	s_mov_b32 s18, 1
	s_mov_b64 s[20:21], 0
	s_branch .LBB0_213

.LBB0_1286:
	s_or_b64 exec, exec, s[12:13]
	v_cvt_f32_u32_e32 v5, v3
	s_waitcnt vmcnt(0)
	v_readfirstlane_b32 s10, v4
	v_sub_u32_e32 v4, 0, v3
	v_rcp_iflag_f32_e32 v5, v5
	v_add_u32_e32 v6, s10, v1
	v_mul_f32_e32 v5, 0x4f7ffffe, v5
	v_cvt_u32_f32_e32 v5, v5
	v_mul_lo_u32 v1, v4, v5
	v_mul_hi_u32 v1, v5, v1
	v_add_u32_e32 v1, v5, v1
	v_mul_hi_u32 v1, v6, v1
	v_mul_lo_u32 v4, v1, v3
	v_sub_u32_e32 v4, v6, v4
	v_add_u32_e32 v5, 1, v1
	v_cmp_ge_u32_e32 vcc, v4, v3
	s_nop 1
	v_cndmask_b32_e32 v1, v1, v5, vcc
	v_sub_u32_e32 v5, v4, v3
	v_cndmask_b32_e32 v4, v4, v5, vcc
	v_add_u32_e32 v5, 1, v1
	v_cmp_ge_u32_e32 vcc, v4, v3
	v_add_u32_e32 v4, 1, v6
	s_nop 0
	v_cndmask_b32_e32 v1, v1, v5, vcc
	v_mul_lo_u32 v5, v3, v1
	v_add_u32_e32 v3, v5, v3
	v_cmp_ne_u32_e32 vcc, v4, v3
	s_and_saveexec_b64 s[10:11], vcc
	s_xor_b64 s[10:11], exec, s[10:11]
	s_mov_b32 s54, 0x8000
	s_cbranch_execz .LBB0_1300
	s_waitcnt lgkmcnt(0)
	v_mov_b32_e32 v2, 0
	buffer_inv sc1
	s_add_u32 s16, s6, 0x13500
	s_addc_u32 s17, s7, 0
	global_load_dword v2, v2, s[16:17] sc1
	s_waitcnt vmcnt(0)
	v_cmp_eq_u32_e32 vcc, v2, v1
	s_and_saveexec_b64 s[12:13], vcc
	s_cbranch_execz .LBB0_1299
	s_add_u32 s14, s6, 0x10200
	s_addc_u32 s15, s7, 0
	s_mov_b32 s38, 1
	s_mov_b64 s[18:19], 0
	s_branch .LBB0_1290

.LBB0_1400:
	s_or_b64 exec, exec, s[12:13]
	v_cvt_f32_u32_e32 v5, v3
	s_waitcnt vmcnt(0)
	v_readfirstlane_b32 s10, v4
	v_sub_u32_e32 v4, 0, v3
	v_rcp_iflag_f32_e32 v5, v5
	v_add_u32_e32 v6, s10, v1
	v_mul_f32_e32 v5, 0x4f7ffffe, v5
	v_cvt_u32_f32_e32 v5, v5
	v_mul_lo_u32 v1, v4, v5
	v_mul_hi_u32 v1, v5, v1
	v_add_u32_e32 v1, v5, v1
	v_mul_hi_u32 v1, v6, v1
	v_mul_lo_u32 v4, v1, v3
	v_sub_u32_e32 v4, v6, v4
	v_add_u32_e32 v5, 1, v1
	v_cmp_ge_u32_e32 vcc, v4, v3
	s_nop 1
	v_cndmask_b32_e32 v1, v1, v5, vcc
	v_sub_u32_e32 v5, v4, v3
	v_cndmask_b32_e32 v4, v4, v5, vcc
	v_add_u32_e32 v5, 1, v1
	v_cmp_ge_u32_e32 vcc, v4, v3
	v_add_u32_e32 v4, 1, v6
	s_nop 0
	v_cndmask_b32_e32 v1, v1, v5, vcc
	v_mul_lo_u32 v5, v3, v1
	v_add_u32_e32 v3, v5, v3
	v_cmp_ne_u32_e32 vcc, v4, v3
	s_and_saveexec_b64 s[10:11], vcc
	s_xor_b64 s[10:11], exec, s[10:11]
	s_cbranch_execz .LBB0_1414
	s_waitcnt lgkmcnt(0)
	v_mov_b32_e32 v2, 0
	buffer_inv sc1
	s_add_u32 s16, s6, 0x13500
	s_addc_u32 s17, s7, 0
	global_load_dword v2, v2, s[16:17] sc1
	s_waitcnt vmcnt(0)
	v_cmp_eq_u32_e32 vcc, v2, v1
	s_and_saveexec_b64 s[12:13], vcc
	s_cbranch_execz .LBB0_1413
	s_add_u32 s14, s6, 0x10200
	s_addc_u32 s15, s7, 0
	s_mov_b32 s38, 1
	s_mov_b64 s[18:19], 0
	s_branch .LBB0_1404
